# stack26 + P4 attention output (A1) stores written through (sc1): seam 4's L2 writeback shrinks
# speedup vs baseline: 1.0052x; 1.0008x over previous
.LBB0_645:
	v_mov_b32_e32 v99, v198
	v_mov_b32_e32 v100, v198
	s_nop 1
	v_permlane32_swap_b32_e32 v99, v100
	v_cndmask_b32_e64 v99, v99, v100, s[4:5]
	v_lshlrev_b32_e32 v98, 16, v181
	v_add_f32_e32 v99, v198, v99
	v_div_scale_f32 v102, s[2:3], v99, v99, v98
	v_rcp_f32_e32 v103, v102
	v_div_scale_f32 v104, vcc, v98, v99, v98
	v_readlane_b32 s2, v246, 33
	v_fma_f32 v100, -v102, v103, 1.0
	v_fmac_f32_e32 v103, v100, v103
	v_mul_f32_e32 v105, v104, v103
	v_fma_f32 v100, -v102, v105, v104
	v_fmac_f32_e32 v105, v100, v103
	ds_read_b64 v[100:101], v190
	v_fma_f32 v102, -v102, v105, v104
	v_div_fmas_f32 v102, v102, v103, v105
	v_div_fixup_f32 v98, v102, v99, v98
	s_mov_b64 s[82:83], 0
	s_waitcnt lgkmcnt(0)
	v_lshlrev_b32_e32 v102, 16, v100
	v_and_b32_e32 v103, 0xffff0000, v100
	v_lshlrev_b32_e32 v100, 16, v101
	v_and_b32_e32 v101, 0xffff0000, v101
	v_pk_fma_f32 v[50:51], v[50:51], v[98:99], v[102:103] op_sel_hi:[1,0,1]
	v_pk_fma_f32 v[52:53], v[52:53], v[98:99], v[100:101] op_sel_hi:[1,0,1]
	v_cvt_pk_bf16_f32 v50, v50, v51
	v_cvt_pk_bf16_f32 v51, v52, v53
	v_add3_u32 v99, s2, v183, v197
	ds_write_b64 v99, v[50:51]
	ds_read_b64 v[50:51], v190 offset:512
	s_waitcnt lgkmcnt(0)
	v_lshlrev_b32_e32 v52, 16, v50
	v_and_b32_e32 v53, 0xffff0000, v50
	v_pk_fma_f32 v[52:53], v[54:55], v[98:99], v[52:53] op_sel_hi:[1,0,1]
	s_nop 0
	v_cvt_pk_bf16_f32 v50, v52, v53
	v_lshlrev_b32_e32 v52, 16, v51
	v_and_b32_e32 v53, 0xffff0000, v51
	v_pk_fma_f32 v[52:53], v[56:57], v[98:99], v[52:53] op_sel_hi:[1,0,1]
	s_nop 0
	v_cvt_pk_bf16_f32 v51, v52, v53
	ds_write_b64 v99, v[50:51] offset:16
	ds_read_b64 v[50:51], v190 offset:1024
	s_waitcnt lgkmcnt(0)
	v_lshlrev_b32_e32 v52, 16, v50
	v_and_b32_e32 v53, 0xffff0000, v50
	v_pk_fma_f32 v[52:53], v[58:59], v[98:99], v[52:53] op_sel_hi:[1,0,1]
	s_nop 0
	v_cvt_pk_bf16_f32 v50, v52, v53
	v_lshlrev_b32_e32 v52, 16, v51
	v_and_b32_e32 v53, 0xffff0000, v51
	v_pk_fma_f32 v[52:53], v[60:61], v[98:99], v[52:53] op_sel_hi:[1,0,1]
	s_nop 0
	v_cvt_pk_bf16_f32 v51, v52, v53
	ds_write_b64 v99, v[50:51] offset:32
	ds_read_b64 v[50:51], v190 offset:1536
	s_waitcnt lgkmcnt(0)
	v_lshlrev_b32_e32 v52, 16, v50
	v_and_b32_e32 v53, 0xffff0000, v50
	v_pk_fma_f32 v[52:53], v[62:63], v[98:99], v[52:53] op_sel_hi:[1,0,1]
	s_nop 0
	v_cvt_pk_bf16_f32 v50, v52, v53
	v_lshlrev_b32_e32 v52, 16, v51
	v_and_b32_e32 v53, 0xffff0000, v51
	v_pk_fma_f32 v[52:53], v[64:65], v[98:99], v[52:53] op_sel_hi:[1,0,1]
	s_nop 0
	v_cvt_pk_bf16_f32 v51, v52, v53
	ds_write_b64 v99, v[50:51] offset:48
	ds_read_b64 v[50:51], v190 offset:2048
	s_waitcnt lgkmcnt(0)
	v_lshlrev_b32_e32 v52, 16, v50
	v_and_b32_e32 v53, 0xffff0000, v50
	v_lshlrev_b32_e32 v50, 16, v51
	v_and_b32_e32 v51, 0xffff0000, v51
	v_pk_fma_f32 v[34:35], v[34:35], v[98:99], v[52:53] op_sel_hi:[1,0,1]
	v_pk_fma_f32 v[36:37], v[36:37], v[98:99], v[50:51] op_sel_hi:[1,0,1]
	v_cvt_pk_bf16_f32 v34, v34, v35
	v_cvt_pk_bf16_f32 v35, v36, v37
	ds_write_b64 v99, v[34:35] offset:64
	ds_read_b64 v[34:35], v190 offset:2560
	s_waitcnt lgkmcnt(0)
	v_lshlrev_b32_e32 v36, 16, v34
	v_and_b32_e32 v37, 0xffff0000, v34
	v_pk_fma_f32 v[36:37], v[38:39], v[98:99], v[36:37] op_sel_hi:[1,0,1]
	s_nop 0
	v_cvt_pk_bf16_f32 v34, v36, v37
	v_lshlrev_b32_e32 v36, 16, v35
	v_and_b32_e32 v37, 0xffff0000, v35
	v_pk_fma_f32 v[36:37], v[40:41], v[98:99], v[36:37] op_sel_hi:[1,0,1]
	s_nop 0
	v_cvt_pk_bf16_f32 v35, v36, v37
	ds_write_b64 v99, v[34:35] offset:80
	ds_read_b64 v[34:35], v190 offset:3072
	s_waitcnt lgkmcnt(0)
	v_lshlrev_b32_e32 v36, 16, v34
	v_and_b32_e32 v37, 0xffff0000, v34
	v_pk_fma_f32 v[36:37], v[42:43], v[98:99], v[36:37] op_sel_hi:[1,0,1]
	s_nop 0
	v_cvt_pk_bf16_f32 v34, v36, v37
	v_lshlrev_b32_e32 v36, 16, v35
	v_and_b32_e32 v37, 0xffff0000, v35
	v_pk_fma_f32 v[36:37], v[44:45], v[98:99], v[36:37] op_sel_hi:[1,0,1]
	s_nop 0
	v_cvt_pk_bf16_f32 v35, v36, v37
	ds_write_b64 v99, v[34:35] offset:96
	ds_read_b64 v[34:35], v190 offset:3584
	s_waitcnt lgkmcnt(0)
	v_lshlrev_b32_e32 v36, 16, v34
	v_and_b32_e32 v37, 0xffff0000, v34
	v_pk_fma_f32 v[36:37], v[46:47], v[98:99], v[36:37] op_sel_hi:[1,0,1]
	s_nop 0
	v_cvt_pk_bf16_f32 v34, v36, v37
	v_lshlrev_b32_e32 v36, 16, v35
	v_and_b32_e32 v37, 0xffff0000, v35
	v_pk_fma_f32 v[36:37], v[48:49], v[98:99], v[36:37] op_sel_hi:[1,0,1]
	s_nop 0
	v_cvt_pk_bf16_f32 v35, v36, v37
	ds_write_b64 v99, v[34:35] offset:112
	ds_read_b64 v[34:35], v190 offset:4096
	s_waitcnt lgkmcnt(0)
	v_lshlrev_b32_e32 v36, 16, v34
	v_and_b32_e32 v37, 0xffff0000, v34
	v_lshlrev_b32_e32 v34, 16, v35
	v_and_b32_e32 v35, 0xffff0000, v35
	v_pk_fma_f32 v[18:19], v[18:19], v[98:99], v[36:37] op_sel_hi:[1,0,1]
	v_pk_fma_f32 v[20:21], v[20:21], v[98:99], v[34:35] op_sel_hi:[1,0,1]
	v_cvt_pk_bf16_f32 v18, v18, v19
	v_cvt_pk_bf16_f32 v19, v20, v21
	ds_write_b64 v99, v[18:19] offset:128
	ds_read_b64 v[18:19], v190 offset:4608
	s_waitcnt lgkmcnt(0)
	v_lshlrev_b32_e32 v20, 16, v18
	v_and_b32_e32 v21, 0xffff0000, v18
	v_pk_fma_f32 v[20:21], v[22:23], v[98:99], v[20:21] op_sel_hi:[1,0,1]
	s_nop 0
	v_cvt_pk_bf16_f32 v18, v20, v21
	v_lshlrev_b32_e32 v20, 16, v19
	v_and_b32_e32 v21, 0xffff0000, v19
	v_pk_fma_f32 v[20:21], v[24:25], v[98:99], v[20:21] op_sel_hi:[1,0,1]
	s_nop 0
	v_cvt_pk_bf16_f32 v19, v20, v21
	ds_write_b64 v99, v[18:19] offset:144
	ds_read_b64 v[18:19], v190 offset:5120
	s_waitcnt lgkmcnt(0)
	v_lshlrev_b32_e32 v20, 16, v18
	v_and_b32_e32 v21, 0xffff0000, v18
	v_pk_fma_f32 v[20:21], v[26:27], v[98:99], v[20:21] op_sel_hi:[1,0,1]
	s_nop 0
	v_cvt_pk_bf16_f32 v18, v20, v21
	v_lshlrev_b32_e32 v20, 16, v19
	v_and_b32_e32 v21, 0xffff0000, v19
	v_pk_fma_f32 v[20:21], v[28:29], v[98:99], v[20:21] op_sel_hi:[1,0,1]
	s_nop 0
	v_cvt_pk_bf16_f32 v19, v20, v21
	ds_write_b64 v99, v[18:19] offset:160
	ds_read_b64 v[18:19], v190 offset:5632
	s_waitcnt lgkmcnt(0)
	v_lshlrev_b32_e32 v20, 16, v18
	v_and_b32_e32 v21, 0xffff0000, v18
	v_pk_fma_f32 v[20:21], v[30:31], v[98:99], v[20:21] op_sel_hi:[1,0,1]
	s_nop 0
	v_cvt_pk_bf16_f32 v18, v20, v21
	v_lshlrev_b32_e32 v20, 16, v19
	v_and_b32_e32 v21, 0xffff0000, v19
	v_pk_fma_f32 v[20:21], v[32:33], v[98:99], v[20:21] op_sel_hi:[1,0,1]
	s_nop 0
	v_cvt_pk_bf16_f32 v19, v20, v21
	ds_write_b64 v99, v[18:19] offset:176
	ds_read_b64 v[18:19], v190 offset:6144
	s_waitcnt lgkmcnt(0)
	v_lshlrev_b32_e32 v20, 16, v18
	v_and_b32_e32 v21, 0xffff0000, v18
	v_lshlrev_b32_e32 v18, 16, v19
	v_and_b32_e32 v19, 0xffff0000, v19
	v_pk_fma_f32 v[2:3], v[2:3], v[98:99], v[20:21] op_sel_hi:[1,0,1]
	v_pk_fma_f32 v[4:5], v[4:5], v[98:99], v[18:19] op_sel_hi:[1,0,1]
	v_cvt_pk_bf16_f32 v2, v2, v3
	v_cvt_pk_bf16_f32 v3, v4, v5
	ds_write_b64 v99, v[2:3] offset:192
	ds_read_b64 v[2:3], v190 offset:6656
	s_waitcnt lgkmcnt(0)
	v_lshlrev_b32_e32 v4, 16, v2
	v_and_b32_e32 v5, 0xffff0000, v2
	v_pk_fma_f32 v[4:5], v[6:7], v[98:99], v[4:5] op_sel_hi:[1,0,1]
	s_nop 0
	v_cvt_pk_bf16_f32 v2, v4, v5
	v_lshlrev_b32_e32 v4, 16, v3
	v_and_b32_e32 v5, 0xffff0000, v3
	v_pk_fma_f32 v[4:5], v[8:9], v[98:99], v[4:5] op_sel_hi:[1,0,1]
	s_nop 0
	v_cvt_pk_bf16_f32 v3, v4, v5
	ds_write_b64 v99, v[2:3] offset:208
	ds_read_b64 v[2:3], v190 offset:7168
	s_waitcnt lgkmcnt(0)
	v_lshlrev_b32_e32 v4, 16, v2
	v_and_b32_e32 v5, 0xffff0000, v2
	v_pk_fma_f32 v[4:5], v[10:11], v[98:99], v[4:5] op_sel_hi:[1,0,1]
	s_nop 0
	v_cvt_pk_bf16_f32 v2, v4, v5
	v_lshlrev_b32_e32 v4, 16, v3
	v_and_b32_e32 v5, 0xffff0000, v3
	v_pk_fma_f32 v[4:5], v[12:13], v[98:99], v[4:5] op_sel_hi:[1,0,1]
	s_nop 0
	v_cvt_pk_bf16_f32 v3, v4, v5
	ds_write_b64 v99, v[2:3] offset:224
	ds_read_b64 v[2:3], v190 offset:7680
	s_waitcnt lgkmcnt(0)
	v_lshlrev_b32_e32 v4, 16, v2
	v_and_b32_e32 v5, 0xffff0000, v2
	v_pk_fma_f32 v[4:5], v[14:15], v[98:99], v[4:5] op_sel_hi:[1,0,1]
	s_waitcnt vmcnt(7)
	v_lshlrev_b32_e32 v14, 16, v94
	v_cvt_pk_bf16_f32 v2, v4, v5
	v_lshlrev_b32_e32 v4, 16, v3
	v_and_b32_e32 v5, 0xffff0000, v3
	v_pk_fma_f32 v[4:5], v[16:17], v[98:99], v[4:5] op_sel_hi:[1,0,1]
	v_and_b32_e32 v15, 0xffff0000, v94
	v_cvt_pk_bf16_f32 v3, v4, v5
	ds_write_b64 v99, v[2:3] offset:240
	v_mul_u32_u24_e32 v2, 0x110, v196
	s_waitcnt lgkmcnt(0)
	v_add3_u32 v16, s2, v191, v2
	ds_read_b128 v[4:7], v16
	ds_read_b128 v[8:11], v16 offset:1088
	v_readlane_b32 s2, v246, 34
	s_add_u32 s2, s2, s1
	v_readlane_b32 s1, v246, 35
	s_waitcnt lgkmcnt(1)
	v_lshlrev_b32_e32 v12, 16, v4
	v_and_b32_e32 v13, 0xffff0000, v4
	v_pk_mul_f32 v[12:13], v[14:15], v[12:13]
	v_lshlrev_b32_e32 v14, 16, v95
	v_cvt_pk_bf16_f32 v4, v12, v13
	v_lshlrev_b32_e32 v12, 16, v5
	v_and_b32_e32 v13, 0xffff0000, v5
	v_and_b32_e32 v15, 0xffff0000, v95
	v_pk_mul_f32 v[12:13], v[14:15], v[12:13]
	v_lshlrev_b32_e32 v14, 16, v96
	v_cvt_pk_bf16_f32 v5, v12, v13
	v_lshlrev_b32_e32 v12, 16, v6
	v_and_b32_e32 v13, 0xffff0000, v6
	v_and_b32_e32 v15, 0xffff0000, v96
	v_pk_mul_f32 v[12:13], v[14:15], v[12:13]
	v_lshlrev_b32_e32 v14, 16, v97
	v_cvt_pk_bf16_f32 v6, v12, v13
	v_lshlrev_b32_e32 v12, 16, v7
	v_and_b32_e32 v13, 0xffff0000, v7
	v_and_b32_e32 v15, 0xffff0000, v97
	s_addc_u32 s3, s1, s6
	v_pk_mul_f32 v[12:13], v[14:15], v[12:13]
	v_lshl_add_u64 v[2:3], s[2:3], 0, v[178:179]
	v_cvt_pk_bf16_f32 v7, v12, v13
	global_store_dwordx4 v[2:3], v[4:7], off sc1
	v_add_co_u32_e32 v12, vcc, s12, v2
	s_waitcnt lgkmcnt(0)
	v_lshlrev_b32_e32 v4, 16, v8
	v_and_b32_e32 v5, 0xffff0000, v8
	s_waitcnt vmcnt(7)
	v_lshlrev_b32_e32 v6, 16, v90
	v_and_b32_e32 v7, 0xffff0000, v90
	v_pk_mul_f32 v[4:5], v[6:7], v[4:5]
	v_lshlrev_b32_e32 v6, 16, v9
	v_and_b32_e32 v7, 0xffff0000, v9
	v_lshlrev_b32_e32 v8, 16, v91
	v_and_b32_e32 v9, 0xffff0000, v91
	v_pk_mul_f32 v[6:7], v[8:9], v[6:7]
	v_cvt_pk_bf16_f32 v4, v4, v5
	v_cvt_pk_bf16_f32 v5, v6, v7
	v_lshlrev_b32_e32 v6, 16, v10
	v_and_b32_e32 v7, 0xffff0000, v10
	v_lshlrev_b32_e32 v8, 16, v92
	v_and_b32_e32 v9, 0xffff0000, v92
	v_pk_mul_f32 v[6:7], v[8:9], v[6:7]
	v_lshlrev_b32_e32 v8, 16, v11
	v_and_b32_e32 v9, 0xffff0000, v11
	v_lshlrev_b32_e32 v10, 16, v93
	v_and_b32_e32 v11, 0xffff0000, v93
	v_pk_mul_f32 v[8:9], v[10:11], v[8:9]
	v_cvt_pk_bf16_f32 v6, v6, v7
	v_cvt_pk_bf16_f32 v7, v8, v9
	ds_read_b128 v[8:11], v16 offset:2176
	v_addc_co_u32_e32 v13, vcc, 0, v3, vcc
	global_store_dwordx4 v[12:13], v[4:7], off sc1
	ds_read_b128 v[4:7], v16 offset:3264
	s_waitcnt lgkmcnt(1)
	v_lshlrev_b32_e32 v12, 16, v8
	v_and_b32_e32 v13, 0xffff0000, v8
	s_waitcnt vmcnt(7)
	v_lshlrev_b32_e32 v14, 16, v86
	v_and_b32_e32 v15, 0xffff0000, v86
	v_pk_mul_f32 v[12:13], v[14:15], v[12:13]
	v_lshlrev_b32_e32 v14, 16, v87
	v_cvt_pk_bf16_f32 v8, v12, v13
	v_lshlrev_b32_e32 v12, 16, v9
	v_and_b32_e32 v13, 0xffff0000, v9
	v_and_b32_e32 v15, 0xffff0000, v87
	v_pk_mul_f32 v[12:13], v[14:15], v[12:13]
	v_lshlrev_b32_e32 v14, 16, v88
	v_cvt_pk_bf16_f32 v9, v12, v13
	v_lshlrev_b32_e32 v12, 16, v10
	v_and_b32_e32 v13, 0xffff0000, v10
	v_and_b32_e32 v15, 0xffff0000, v88
	v_pk_mul_f32 v[12:13], v[14:15], v[12:13]
	v_lshlrev_b32_e32 v14, 16, v89
	v_cvt_pk_bf16_f32 v10, v12, v13
	v_lshlrev_b32_e32 v12, 16, v11
	v_and_b32_e32 v13, 0xffff0000, v11
	v_and_b32_e32 v15, 0xffff0000, v89
	v_pk_mul_f32 v[12:13], v[14:15], v[12:13]
	s_waitcnt vmcnt(5)
	v_lshlrev_b32_e32 v14, 16, v74
	v_cvt_pk_bf16_f32 v11, v12, v13
	v_add_co_u32_e32 v12, vcc, s13, v2
	v_and_b32_e32 v15, 0xffff0000, v74
	s_nop 0
	v_addc_co_u32_e32 v13, vcc, 0, v3, vcc
	global_store_dwordx4 v[12:13], v[8:11], off sc1
	v_add_co_u32_e32 v12, vcc, s14, v2
	s_waitcnt lgkmcnt(0)
	v_lshlrev_b32_e32 v8, 16, v4
	v_and_b32_e32 v9, 0xffff0000, v4
	v_lshlrev_b32_e32 v10, 16, v82
	v_and_b32_e32 v11, 0xffff0000, v82
	v_pk_mul_f32 v[8:9], v[10:11], v[8:9]
	v_lshlrev_b32_e32 v10, 16, v83
	v_cvt_pk_bf16_f32 v4, v8, v9
	v_lshlrev_b32_e32 v8, 16, v5
	v_and_b32_e32 v9, 0xffff0000, v5
	v_and_b32_e32 v11, 0xffff0000, v83
	v_pk_mul_f32 v[8:9], v[10:11], v[8:9]
	v_lshlrev_b32_e32 v10, 16, v84
	v_cvt_pk_bf16_f32 v5, v8, v9
	v_lshlrev_b32_e32 v8, 16, v6
	v_and_b32_e32 v9, 0xffff0000, v6
	v_and_b32_e32 v11, 0xffff0000, v84
	v_pk_mul_f32 v[8:9], v[10:11], v[8:9]
	v_lshlrev_b32_e32 v10, 16, v85
	v_cvt_pk_bf16_f32 v6, v8, v9
	v_lshlrev_b32_e32 v8, 16, v7
	v_and_b32_e32 v9, 0xffff0000, v7
	v_and_b32_e32 v11, 0xffff0000, v85
	v_pk_mul_f32 v[8:9], v[10:11], v[8:9]
	v_addc_co_u32_e32 v13, vcc, 0, v3, vcc
	v_cvt_pk_bf16_f32 v7, v8, v9
	ds_read_b128 v[8:11], v16 offset:4352
	global_store_dwordx4 v[12:13], v[4:7], off sc1
	ds_read_b128 v[4:7], v16 offset:5440
	s_waitcnt lgkmcnt(1)
	v_lshlrev_b32_e32 v12, 16, v8
	v_and_b32_e32 v13, 0xffff0000, v8
	v_pk_mul_f32 v[12:13], v[14:15], v[12:13]
	v_lshlrev_b32_e32 v14, 16, v75
	v_cvt_pk_bf16_f32 v8, v12, v13
	v_lshlrev_b32_e32 v12, 16, v9
	v_and_b32_e32 v13, 0xffff0000, v9
	v_and_b32_e32 v15, 0xffff0000, v75
	v_pk_mul_f32 v[12:13], v[14:15], v[12:13]
	v_lshlrev_b32_e32 v14, 16, v76
	v_cvt_pk_bf16_f32 v9, v12, v13
	v_lshlrev_b32_e32 v12, 16, v10
	v_and_b32_e32 v13, 0xffff0000, v10
	v_and_b32_e32 v15, 0xffff0000, v76
	v_pk_mul_f32 v[12:13], v[14:15], v[12:13]
	v_lshlrev_b32_e32 v14, 16, v77
	v_cvt_pk_bf16_f32 v10, v12, v13
	v_lshlrev_b32_e32 v12, 16, v11
	v_and_b32_e32 v13, 0xffff0000, v11
	v_and_b32_e32 v15, 0xffff0000, v77
	v_pk_mul_f32 v[12:13], v[14:15], v[12:13]
	s_waitcnt vmcnt(5)
	v_lshlrev_b32_e32 v14, 16, v70
	v_cvt_pk_bf16_f32 v11, v12, v13
	v_add_co_u32_e32 v12, vcc, s15, v2
	v_and_b32_e32 v15, 0xffff0000, v70
	s_nop 0
	v_addc_co_u32_e32 v13, vcc, 0, v3, vcc
	global_store_dwordx4 v[12:13], v[8:11], off sc1
	v_add_co_u32_e32 v12, vcc, s16, v2
	s_waitcnt lgkmcnt(0)
	v_lshlrev_b32_e32 v8, 16, v4
	v_and_b32_e32 v9, 0xffff0000, v4
	v_lshlrev_b32_e32 v10, 16, v78
	v_and_b32_e32 v11, 0xffff0000, v78
	v_pk_mul_f32 v[8:9], v[10:11], v[8:9]
	v_lshlrev_b32_e32 v10, 16, v79
	v_cvt_pk_bf16_f32 v4, v8, v9
	v_lshlrev_b32_e32 v8, 16, v5
	v_and_b32_e32 v9, 0xffff0000, v5
	v_and_b32_e32 v11, 0xffff0000, v79
	v_pk_mul_f32 v[8:9], v[10:11], v[8:9]
	v_lshlrev_b32_e32 v10, 16, v80
	v_cvt_pk_bf16_f32 v5, v8, v9
	v_lshlrev_b32_e32 v8, 16, v6
	v_and_b32_e32 v9, 0xffff0000, v6
	v_and_b32_e32 v11, 0xffff0000, v80
	v_pk_mul_f32 v[8:9], v[10:11], v[8:9]
	v_lshlrev_b32_e32 v10, 16, v81
	v_cvt_pk_bf16_f32 v6, v8, v9
	v_lshlrev_b32_e32 v8, 16, v7
	v_and_b32_e32 v9, 0xffff0000, v7
	v_and_b32_e32 v11, 0xffff0000, v81
	v_pk_mul_f32 v[8:9], v[10:11], v[8:9]
	v_addc_co_u32_e32 v13, vcc, 0, v3, vcc
	v_cvt_pk_bf16_f32 v7, v8, v9
	ds_read_b128 v[8:11], v16 offset:6528
	global_store_dwordx4 v[12:13], v[4:7], off sc1
	ds_read_b128 v[4:7], v16 offset:7616
	s_waitcnt lgkmcnt(1)
	v_lshlrev_b32_e32 v12, 16, v8
	v_and_b32_e32 v13, 0xffff0000, v8
	v_pk_mul_f32 v[12:13], v[14:15], v[12:13]
	v_lshlrev_b32_e32 v14, 16, v71
	v_cvt_pk_bf16_f32 v8, v12, v13
	v_lshlrev_b32_e32 v12, 16, v9
	v_and_b32_e32 v13, 0xffff0000, v9
	v_and_b32_e32 v15, 0xffff0000, v71
	v_pk_mul_f32 v[12:13], v[14:15], v[12:13]
	v_lshlrev_b32_e32 v14, 16, v72
	v_cvt_pk_bf16_f32 v9, v12, v13
	v_lshlrev_b32_e32 v12, 16, v10
	v_and_b32_e32 v13, 0xffff0000, v10
	v_and_b32_e32 v15, 0xffff0000, v72
	v_pk_mul_f32 v[12:13], v[14:15], v[12:13]
	v_lshlrev_b32_e32 v14, 16, v73
	v_cvt_pk_bf16_f32 v10, v12, v13
	v_lshlrev_b32_e32 v12, 16, v11
	v_and_b32_e32 v13, 0xffff0000, v11
	v_and_b32_e32 v15, 0xffff0000, v73
	v_pk_mul_f32 v[12:13], v[14:15], v[12:13]
	s_nop 0
	v_cvt_pk_bf16_f32 v11, v12, v13
	v_add_co_u32_e32 v12, vcc, s17, v2
	s_nop 1
	v_addc_co_u32_e32 v13, vcc, 0, v3, vcc
	global_store_dwordx4 v[12:13], v[8:11], off sc1
	v_add_co_u32_e32 v2, vcc, 0x1c000, v2
	s_waitcnt lgkmcnt(0)
	v_lshlrev_b32_e32 v8, 16, v4
	v_and_b32_e32 v9, 0xffff0000, v4
	s_waitcnt vmcnt(7)
	v_lshlrev_b32_e32 v10, 16, v66
	v_and_b32_e32 v11, 0xffff0000, v66
	v_pk_mul_f32 v[8:9], v[10:11], v[8:9]
	v_lshlrev_b32_e32 v10, 16, v67
	v_cvt_pk_bf16_f32 v4, v8, v9
	v_lshlrev_b32_e32 v8, 16, v5
	v_and_b32_e32 v9, 0xffff0000, v5
	v_and_b32_e32 v11, 0xffff0000, v67
	v_pk_mul_f32 v[8:9], v[10:11], v[8:9]
	v_lshlrev_b32_e32 v10, 16, v68
	v_cvt_pk_bf16_f32 v5, v8, v9
	v_lshlrev_b32_e32 v8, 16, v6
	v_and_b32_e32 v9, 0xffff0000, v6
	v_and_b32_e32 v11, 0xffff0000, v68
	v_pk_mul_f32 v[8:9], v[10:11], v[8:9]
	v_lshlrev_b32_e32 v10, 16, v69
	v_cvt_pk_bf16_f32 v6, v8, v9
	v_lshlrev_b32_e32 v8, 16, v7
	v_and_b32_e32 v9, 0xffff0000, v7
	v_and_b32_e32 v11, 0xffff0000, v69
	v_pk_mul_f32 v[8:9], v[10:11], v[8:9]
	v_addc_co_u32_e32 v3, vcc, 0, v3, vcc
	v_cvt_pk_bf16_f32 v7, v8, v9
	s_and_b64 vcc, exec, s[80:81]
	global_store_dwordx4 v[2:3], v[4:7], off sc1
	s_barrier
	s_cbranch_vccnz .LBB0_643
